# EpiGU epilogue hand-rewritten: packed f32 math, no register shuffles, two row-blocks interleaved (same f32 formula)
# speedup vs baseline: 1.0233x; 1.0233x over previous
; #define LAS __attribute__((address_space(3)))
; __device__ __forceinline__ float siluf_(float x) { return x * sigmoidf_(x); }
; __device__ __forceinline__ void rows_rstd(LAS unsigned char* sl, int rl0, int fq, float (&rs)[8]) {
;     f32x4 v[8];
; #pragma unroll
;     for (int i = 0; i < 8; ++i) v[i] = *(const LAS f32x4*)(sl + (rl0 + (i >> 2) * 128 + (i & 3) * 16) * 64 + fq * 16);
; #pragma unroll
;     for (int i = 0; i < 8; ++i) { float s = (v[i].x + v[i].y) + (v[i].z + v[i].w); s += __shfl_xor(s, 16); s += __shfl_xor(s, 32); rs[i] = rsqrtf(s * (1.0f / DM) + EPS); }
; }
;     __device__ __forceinline__ void operator()(const f32x4 (&acc)[2][2][4][2], const pg8::Unit& u, int wr, int wc, int fr, int fq) const {
;         const int row0 = u.pm * 256 + wr * 64 + fr, col0 = u.pn * 128 + wc * 32 + 8 * fq;
;         float rs[8]; rows_rstd(sl, wr * 64 + fr, fq, rs);
; #pragma unroll
;         for (int ai = 0; ai < 2; ++ai)
; #pragma unroll
;             for (int m = 0; m < 4; ++m) {
;                 const int row = row0 + ai * 128 + m * 16; const float r = rs[ai * 4 + m];
;                 float h[8];
; #pragma unroll
;                 for (int n = 0; n < 2; ++n)
; #pragma unroll
;                     for (int j = 0; j < 4; ++j) { const float g = acc[ai][0][m][n][j] * r, up = acc[ai][1][m][n][j] * r; h[n * 4 + j] = siluf_(g) * up; }
.LBB0_1652:
	v_xor_b32_e32 v130, 16, v175
	v_xor_b32_e32 v131, 32, v175
	ds_read_b128 v[200:203], v198
	ds_read_b128 v[204:207], v198 offset:1024
	ds_read_b128 v[208:211], v198 offset:2048
	ds_read_b128 v[212:215], v198 offset:3072
	ds_read_b128 v[216:219], v198 offset:8192
	ds_read_b128 v[220:223], v198 offset:9216
	ds_read_b128 v[224:227], v198 offset:10240
	ds_read_b128 v[228:231], v198 offset:11264
	v_lshlrev_b32_e32 v130, 2, v130
	v_lshlrev_b32_e32 v131, 2, v131
	v_mov_b32_e32 v128, 1.0
	v_mov_b32_e32 v129, 1.0
	v_mov_b32_e32 v134, 0xbfb8aa3b
	v_mov_b32_e32 v135, 0x3a800000
	v_add_u32_e32 v132, s45, v163
	v_mul_u32_u24_e32 v132, 0x1600, v132
	v_lshl_or_b32 v133, s38, 7, v171
	v_lshl_add_u32 v132, v133, 1, v132
	s_waitcnt lgkmcnt(0)
	v_add_f32_e32 v232, v200, v201
	v_add_f32_e32 v233, v204, v205
	v_add_f32_e32 v234, v208, v209
	v_add_f32_e32 v235, v212, v213
	v_add_f32_e32 v236, v216, v217
	v_add_f32_e32 v237, v220, v221
	v_add_f32_e32 v238, v224, v225
	v_add_f32_e32 v239, v228, v229
	v_add_f32_e32 v240, v202, v203
	v_add_f32_e32 v241, v206, v207
	v_add_f32_e32 v242, v210, v211
	v_add_f32_e32 v243, v214, v215
	v_add_f32_e32 v244, v218, v219
	v_add_f32_e32 v245, v222, v223
	v_add_f32_e32 v246, v226, v227
	v_add_f32_e32 v247, v230, v231
	v_add_f32_e32 v232, v232, v240
	v_add_f32_e32 v233, v233, v241
	v_add_f32_e32 v234, v234, v242
	v_add_f32_e32 v235, v235, v243
	v_add_f32_e32 v236, v236, v244
	v_add_f32_e32 v237, v237, v245
	v_add_f32_e32 v238, v238, v246
	v_add_f32_e32 v239, v239, v247
	ds_bpermute_b32 v240, v130, v232
	ds_bpermute_b32 v241, v130, v233
	ds_bpermute_b32 v242, v130, v234
	ds_bpermute_b32 v243, v130, v235
	ds_bpermute_b32 v244, v130, v236
	ds_bpermute_b32 v245, v130, v237
	ds_bpermute_b32 v246, v130, v238
	ds_bpermute_b32 v247, v130, v239
	s_waitcnt lgkmcnt(0)
	v_add_f32_e32 v232, v232, v240
	v_add_f32_e32 v233, v233, v241
	v_add_f32_e32 v234, v234, v242
	v_add_f32_e32 v235, v235, v243
	v_add_f32_e32 v236, v236, v244
	v_add_f32_e32 v237, v237, v245
	v_add_f32_e32 v238, v238, v246
	v_add_f32_e32 v239, v239, v247
	ds_bpermute_b32 v240, v131, v232
	ds_bpermute_b32 v241, v131, v233
	ds_bpermute_b32 v242, v131, v234
	ds_bpermute_b32 v243, v131, v235
	ds_bpermute_b32 v244, v131, v236
	ds_bpermute_b32 v245, v131, v237
	ds_bpermute_b32 v246, v131, v238
	ds_bpermute_b32 v247, v131, v239
	s_waitcnt lgkmcnt(0)
	v_add_f32_e32 v232, v232, v240
	v_add_f32_e32 v233, v233, v241
	v_add_f32_e32 v234, v234, v242
	v_add_f32_e32 v235, v235, v243
	v_add_f32_e32 v236, v236, v244
	v_add_f32_e32 v237, v237, v245
	v_add_f32_e32 v238, v238, v246
	v_add_f32_e32 v239, v239, v247
	v_fmaak_f32 v232, v135, v232, 0x358637bd
	v_fmaak_f32 v233, v135, v233, 0x358637bd
	v_fmaak_f32 v234, v135, v234, 0x358637bd
	v_fmaak_f32 v235, v135, v235, 0x358637bd
	v_fmaak_f32 v236, v135, v236, 0x358637bd
	v_fmaak_f32 v237, v135, v237, 0x358637bd
	v_fmaak_f32 v238, v135, v238, 0x358637bd
	v_fmaak_f32 v239, v135, v239, 0x358637bd
	v_rsq_f32_e32 v200, v232
	v_rsq_f32_e32 v202, v233
	v_rsq_f32_e32 v204, v234
	v_rsq_f32_e32 v206, v235
	v_rsq_f32_e32 v208, v236
	v_rsq_f32_e32 v210, v237
	v_rsq_f32_e32 v212, v238
	v_rsq_f32_e32 v214, v239
	s_nop 0
	v_pk_mul_f32 v[124:125], v[124:125], v[200:201] op_sel_hi:[1,0]
	v_pk_mul_f32 v[126:127], v[126:127], v[200:201] op_sel_hi:[1,0]
	v_pk_mul_f32 v[116:117], v[116:117], v[200:201] op_sel_hi:[1,0]
	v_pk_mul_f32 v[118:119], v[118:119], v[200:201] op_sel_hi:[1,0]
	v_pk_mul_f32 v[108:109], v[108:109], v[202:203] op_sel_hi:[1,0]
	v_pk_mul_f32 v[110:111], v[110:111], v[202:203] op_sel_hi:[1,0]
	v_pk_mul_f32 v[100:101], v[100:101], v[202:203] op_sel_hi:[1,0]
	v_pk_mul_f32 v[102:103], v[102:103], v[202:203] op_sel_hi:[1,0]
	v_pk_mul_f32 v[120:121], v[120:121], v[200:201] op_sel_hi:[1,0]
	v_pk_mul_f32 v[122:123], v[122:123], v[200:201] op_sel_hi:[1,0]
	v_pk_mul_f32 v[112:113], v[112:113], v[200:201] op_sel_hi:[1,0]
	v_pk_mul_f32 v[114:115], v[114:115], v[200:201] op_sel_hi:[1,0]
	v_pk_mul_f32 v[104:105], v[104:105], v[202:203] op_sel_hi:[1,0]
	v_pk_mul_f32 v[106:107], v[106:107], v[202:203] op_sel_hi:[1,0]
	v_pk_mul_f32 v[96:97], v[96:97], v[202:203] op_sel_hi:[1,0]
	v_pk_mul_f32 v[98:99], v[98:99], v[202:203] op_sel_hi:[1,0]
	v_pk_mul_f32 v[120:121], v[124:125], v[120:121]
	v_pk_mul_f32 v[122:123], v[126:127], v[122:123]
	v_pk_mul_f32 v[112:113], v[116:117], v[112:113]
	v_pk_mul_f32 v[114:115], v[118:119], v[114:115]
	v_pk_mul_f32 v[104:105], v[108:109], v[104:105]
	v_pk_mul_f32 v[106:107], v[110:111], v[106:107]
	v_pk_mul_f32 v[96:97], v[100:101], v[96:97]
	v_pk_mul_f32 v[98:99], v[102:103], v[98:99]
	v_pk_mul_f32 v[124:125], v[124:125], v[134:135] op_sel_hi:[1,0]
	v_pk_mul_f32 v[126:127], v[126:127], v[134:135] op_sel_hi:[1,0]
	v_pk_mul_f32 v[116:117], v[116:117], v[134:135] op_sel_hi:[1,0]
	v_pk_mul_f32 v[118:119], v[118:119], v[134:135] op_sel_hi:[1,0]
	v_pk_mul_f32 v[108:109], v[108:109], v[134:135] op_sel_hi:[1,0]
	v_pk_mul_f32 v[110:111], v[110:111], v[134:135] op_sel_hi:[1,0]
	v_pk_mul_f32 v[100:101], v[100:101], v[134:135] op_sel_hi:[1,0]
	v_pk_mul_f32 v[102:103], v[102:103], v[134:135] op_sel_hi:[1,0]
	v_exp_f32_e32 v124, v124
	v_exp_f32_e32 v125, v125
	v_exp_f32_e32 v126, v126
	v_exp_f32_e32 v127, v127
	v_exp_f32_e32 v116, v116
	v_exp_f32_e32 v117, v117
	v_exp_f32_e32 v118, v118
	v_exp_f32_e32 v119, v119
	v_exp_f32_e32 v108, v108
	v_exp_f32_e32 v109, v109
	v_exp_f32_e32 v110, v110
	v_exp_f32_e32 v111, v111
	v_exp_f32_e32 v100, v100
	v_exp_f32_e32 v101, v101
	v_exp_f32_e32 v102, v102
	v_exp_f32_e32 v103, v103
	v_pk_add_f32 v[124:125], v[124:125], v[128:129]
	v_pk_add_f32 v[126:127], v[126:127], v[128:129]
; __device__ __forceinline__ unsigned pk2(float lo, float hi) { return pg8::cvt_pk_bf16(lo, hi); }
; __device__ __forceinline__ float siluf_(float x) { return x * sigmoidf_(x); }
;     __device__ __forceinline__ void operator()(const f32x4 (&acc)[2][2][4][2], const pg8::Unit& u, int wr, int wc, int fr, int fq) const {
;     ...
;             for (int m = 0; m < 4; ++m) {
;                 const int row = row0 + ai * 128 + m * 16; const float r = rs[ai * 4 + m];
;                 float h[8];
; #pragma unroll
;                 for (int n = 0; n < 2; ++n)
; #pragma unroll
;                     for (int j = 0; j < 4; ++j) { const float g = acc[ai][0][m][n][j] * r, up = acc[ai][1][m][n][j] * r; h[n * 4 + j] = siluf_(g) * up; }
;                 u32x4 w; w.x = pk2(h[0], h[1]); w.y = pk2(h[2], h[3]); w.z = pk2(h[4], h[5]); w.w = pk2(h[6], h[7]);
;                 *(u32x4*)(H + (size_t)row * FF + col0) = w;
	v_pk_add_f32 v[116:117], v[116:117], v[128:129]
	v_pk_add_f32 v[118:119], v[118:119], v[128:129]
	v_pk_add_f32 v[108:109], v[108:109], v[128:129]
	v_pk_add_f32 v[110:111], v[110:111], v[128:129]
	v_pk_add_f32 v[100:101], v[100:101], v[128:129]
	v_pk_add_f32 v[102:103], v[102:103], v[128:129]
	v_rcp_f32_e32 v124, v124
	v_rcp_f32_e32 v125, v125
	v_rcp_f32_e32 v126, v126
	v_rcp_f32_e32 v127, v127
	v_rcp_f32_e32 v116, v116
	v_rcp_f32_e32 v117, v117
	v_rcp_f32_e32 v118, v118
	v_rcp_f32_e32 v119, v119
	v_rcp_f32_e32 v108, v108
	v_rcp_f32_e32 v109, v109
	v_rcp_f32_e32 v110, v110
	v_rcp_f32_e32 v111, v111
	v_rcp_f32_e32 v100, v100
	v_rcp_f32_e32 v101, v101
	v_rcp_f32_e32 v102, v102
	v_rcp_f32_e32 v103, v103
	v_pk_mul_f32 v[120:121], v[120:121], v[124:125]
	v_pk_mul_f32 v[122:123], v[122:123], v[126:127]
	v_pk_mul_f32 v[112:113], v[112:113], v[116:117]
	v_pk_mul_f32 v[114:115], v[114:115], v[118:119]
	v_pk_mul_f32 v[104:105], v[104:105], v[108:109]
	v_pk_mul_f32 v[106:107], v[106:107], v[110:111]
	v_pk_mul_f32 v[96:97], v[96:97], v[100:101]
	v_pk_mul_f32 v[98:99], v[98:99], v[102:103]
	v_cvt_pk_bf16_f32 v124, v120, v121
	v_cvt_pk_bf16_f32 v125, v122, v123
	v_cvt_pk_bf16_f32 v126, v112, v113
	v_cvt_pk_bf16_f32 v127, v114, v115
	v_cvt_pk_bf16_f32 v108, v104, v105
	v_cvt_pk_bf16_f32 v109, v106, v107
	v_cvt_pk_bf16_f32 v110, v96, v97
	v_cvt_pk_bf16_f32 v111, v98, v99
	v_mov_b32_e32 v136, v132
	global_store_dwordx4 v136, v[124:127], s[8:9]
	v_add_u32_e32 v137, 0x16000, v132
	global_store_dwordx4 v137, v[108:111], s[8:9]
	v_pk_mul_f32 v[92:93], v[92:93], v[204:205] op_sel_hi:[1,0]
	v_pk_mul_f32 v[94:95], v[94:95], v[204:205] op_sel_hi:[1,0]
	v_pk_mul_f32 v[84:85], v[84:85], v[204:205] op_sel_hi:[1,0]
	v_pk_mul_f32 v[86:87], v[86:87], v[204:205] op_sel_hi:[1,0]
	v_pk_mul_f32 v[76:77], v[76:77], v[206:207] op_sel_hi:[1,0]
	v_pk_mul_f32 v[78:79], v[78:79], v[206:207] op_sel_hi:[1,0]
	v_pk_mul_f32 v[68:69], v[68:69], v[206:207] op_sel_hi:[1,0]
	v_pk_mul_f32 v[70:71], v[70:71], v[206:207] op_sel_hi:[1,0]
	v_pk_mul_f32 v[88:89], v[88:89], v[204:205] op_sel_hi:[1,0]
	v_pk_mul_f32 v[90:91], v[90:91], v[204:205] op_sel_hi:[1,0]
	v_pk_mul_f32 v[80:81], v[80:81], v[204:205] op_sel_hi:[1,0]
	v_pk_mul_f32 v[82:83], v[82:83], v[204:205] op_sel_hi:[1,0]
	v_pk_mul_f32 v[72:73], v[72:73], v[206:207] op_sel_hi:[1,0]
	v_pk_mul_f32 v[74:75], v[74:75], v[206:207] op_sel_hi:[1,0]
	v_pk_mul_f32 v[64:65], v[64:65], v[206:207] op_sel_hi:[1,0]
	v_pk_mul_f32 v[66:67], v[66:67], v[206:207] op_sel_hi:[1,0]
	v_pk_mul_f32 v[88:89], v[92:93], v[88:89]
	v_pk_mul_f32 v[90:91], v[94:95], v[90:91]
	v_pk_mul_f32 v[80:81], v[84:85], v[80:81]
	v_pk_mul_f32 v[82:83], v[86:87], v[82:83]
	v_pk_mul_f32 v[72:73], v[76:77], v[72:73]
	v_pk_mul_f32 v[74:75], v[78:79], v[74:75]
	v_pk_mul_f32 v[64:65], v[68:69], v[64:65]
	v_pk_mul_f32 v[66:67], v[70:71], v[66:67]
	v_pk_mul_f32 v[92:93], v[92:93], v[134:135] op_sel_hi:[1,0]
	v_pk_mul_f32 v[94:95], v[94:95], v[134:135] op_sel_hi:[1,0]
	v_pk_mul_f32 v[84:85], v[84:85], v[134:135] op_sel_hi:[1,0]
	v_pk_mul_f32 v[86:87], v[86:87], v[134:135] op_sel_hi:[1,0]
	v_pk_mul_f32 v[76:77], v[76:77], v[134:135] op_sel_hi:[1,0]
	v_pk_mul_f32 v[78:79], v[78:79], v[134:135] op_sel_hi:[1,0]
	v_pk_mul_f32 v[68:69], v[68:69], v[134:135] op_sel_hi:[1,0]
	v_pk_mul_f32 v[70:71], v[70:71], v[134:135] op_sel_hi:[1,0]
	v_exp_f32_e32 v92, v92
	v_exp_f32_e32 v93, v93
	v_exp_f32_e32 v94, v94
	v_exp_f32_e32 v95, v95
	v_exp_f32_e32 v84, v84
	v_exp_f32_e32 v85, v85
	v_exp_f32_e32 v86, v86
	v_exp_f32_e32 v87, v87
	v_exp_f32_e32 v76, v76
	v_exp_f32_e32 v77, v77
	v_exp_f32_e32 v78, v78
	v_exp_f32_e32 v79, v79
	v_exp_f32_e32 v68, v68
	v_exp_f32_e32 v69, v69
	v_exp_f32_e32 v70, v70
	v_exp_f32_e32 v71, v71
	v_pk_add_f32 v[92:93], v[92:93], v[128:129]
	v_pk_add_f32 v[94:95], v[94:95], v[128:129]
	v_pk_add_f32 v[84:85], v[84:85], v[128:129]
	v_pk_add_f32 v[86:87], v[86:87], v[128:129]
	v_pk_add_f32 v[76:77], v[76:77], v[128:129]
	v_pk_add_f32 v[78:79], v[78:79], v[128:129]
	v_pk_add_f32 v[68:69], v[68:69], v[128:129]
	v_pk_add_f32 v[70:71], v[70:71], v[128:129]
	v_rcp_f32_e32 v92, v92
	v_rcp_f32_e32 v93, v93
	v_rcp_f32_e32 v94, v94
	v_rcp_f32_e32 v95, v95
	v_rcp_f32_e32 v84, v84
	v_rcp_f32_e32 v85, v85
	v_rcp_f32_e32 v86, v86
	v_rcp_f32_e32 v87, v87
	v_rcp_f32_e32 v76, v76
	v_rcp_f32_e32 v77, v77
	v_rcp_f32_e32 v78, v78
	v_rcp_f32_e32 v79, v79
	v_rcp_f32_e32 v68, v68
	v_rcp_f32_e32 v69, v69
	v_rcp_f32_e32 v70, v70
	v_rcp_f32_e32 v71, v71
	v_pk_mul_f32 v[88:89], v[88:89], v[92:93]
	v_pk_mul_f32 v[90:91], v[90:91], v[94:95]
	v_pk_mul_f32 v[80:81], v[80:81], v[84:85]
	v_pk_mul_f32 v[82:83], v[82:83], v[86:87]
	v_pk_mul_f32 v[72:73], v[72:73], v[76:77]
	v_pk_mul_f32 v[74:75], v[74:75], v[78:79]
	v_pk_mul_f32 v[64:65], v[64:65], v[68:69]
	v_pk_mul_f32 v[66:67], v[66:67], v[70:71]
	v_cvt_pk_bf16_f32 v92, v88, v89
	v_cvt_pk_bf16_f32 v93, v90, v91
	v_cvt_pk_bf16_f32 v94, v80, v81
	v_cvt_pk_bf16_f32 v95, v82, v83
	v_cvt_pk_bf16_f32 v76, v72, v73
	v_cvt_pk_bf16_f32 v77, v74, v75
	v_cvt_pk_bf16_f32 v78, v64, v65
	v_cvt_pk_bf16_f32 v79, v66, v67
	v_add_u32_e32 v138, 0x2c000, v132
	global_store_dwordx4 v138, v[92:95], s[8:9]
	v_add_u32_e32 v139, 0x42000, v132
	global_store_dwordx4 v139, v[76:79], s[8:9]
	v_pk_mul_f32 v[60:61], v[60:61], v[208:209] op_sel_hi:[1,0]
	v_pk_mul_f32 v[62:63], v[62:63], v[208:209] op_sel_hi:[1,0]
	v_pk_mul_f32 v[52:53], v[52:53], v[208:209] op_sel_hi:[1,0]
	v_pk_mul_f32 v[54:55], v[54:55], v[208:209] op_sel_hi:[1,0]
	v_pk_mul_f32 v[44:45], v[44:45], v[210:211] op_sel_hi:[1,0]
	v_pk_mul_f32 v[46:47], v[46:47], v[210:211] op_sel_hi:[1,0]
	v_pk_mul_f32 v[36:37], v[36:37], v[210:211] op_sel_hi:[1,0]
; __device__ __forceinline__ unsigned pk2(float lo, float hi) { return pg8::cvt_pk_bf16(lo, hi); }
; __device__ __forceinline__ float siluf_(float x) { return x * sigmoidf_(x); }
; template <class Epi, class Sched, bool ALIGN_EPI = false, bool SP2 = false>
; __device__ __forceinline__ void gemm_phase(PG8_LAS unsigned char* lds, const Gemm g, const Sched& S, const Epi& E) {
;     ...
;         if constexpr (!Epi::AFTER_DRAIN) { E(acc, cur, wr, wc, fr, fq); S.done(cur); }
;         if (!has_next) break;
;     __device__ __forceinline__ void operator()(const f32x4 (&acc)[2][2][4][2], const pg8::Unit& u, int wr, int wc, int fr, int fq) const {
;     ...
;             for (int m = 0; m < 4; ++m) {
;                 const int row = row0 + ai * 128 + m * 16; const float r = rs[ai * 4 + m];
;                 float h[8];
; #pragma unroll
;                 for (int n = 0; n < 2; ++n)
; #pragma unroll
;                     for (int j = 0; j < 4; ++j) { const float g = acc[ai][0][m][n][j] * r, up = acc[ai][1][m][n][j] * r; h[n * 4 + j] = siluf_(g) * up; }
;                 u32x4 w; w.x = pk2(h[0], h[1]); w.y = pk2(h[2], h[3]); w.z = pk2(h[4], h[5]); w.w = pk2(h[6], h[7]);
;                 *(u32x4*)(H + (size_t)row * FF + col0) = w;
	v_pk_mul_f32 v[38:39], v[38:39], v[210:211] op_sel_hi:[1,0]
	v_pk_mul_f32 v[56:57], v[56:57], v[208:209] op_sel_hi:[1,0]
	v_pk_mul_f32 v[58:59], v[58:59], v[208:209] op_sel_hi:[1,0]
	v_pk_mul_f32 v[48:49], v[48:49], v[208:209] op_sel_hi:[1,0]
	v_pk_mul_f32 v[50:51], v[50:51], v[208:209] op_sel_hi:[1,0]
	v_pk_mul_f32 v[40:41], v[40:41], v[210:211] op_sel_hi:[1,0]
	v_pk_mul_f32 v[42:43], v[42:43], v[210:211] op_sel_hi:[1,0]
	v_pk_mul_f32 v[32:33], v[32:33], v[210:211] op_sel_hi:[1,0]
	v_pk_mul_f32 v[34:35], v[34:35], v[210:211] op_sel_hi:[1,0]
	v_pk_mul_f32 v[56:57], v[60:61], v[56:57]
	v_pk_mul_f32 v[58:59], v[62:63], v[58:59]
	v_pk_mul_f32 v[48:49], v[52:53], v[48:49]
	v_pk_mul_f32 v[50:51], v[54:55], v[50:51]
	v_pk_mul_f32 v[40:41], v[44:45], v[40:41]
	v_pk_mul_f32 v[42:43], v[46:47], v[42:43]
	v_pk_mul_f32 v[32:33], v[36:37], v[32:33]
	v_pk_mul_f32 v[34:35], v[38:39], v[34:35]
	v_pk_mul_f32 v[60:61], v[60:61], v[134:135] op_sel_hi:[1,0]
	v_pk_mul_f32 v[62:63], v[62:63], v[134:135] op_sel_hi:[1,0]
	v_pk_mul_f32 v[52:53], v[52:53], v[134:135] op_sel_hi:[1,0]
	v_pk_mul_f32 v[54:55], v[54:55], v[134:135] op_sel_hi:[1,0]
	v_pk_mul_f32 v[44:45], v[44:45], v[134:135] op_sel_hi:[1,0]
	v_pk_mul_f32 v[46:47], v[46:47], v[134:135] op_sel_hi:[1,0]
	v_pk_mul_f32 v[36:37], v[36:37], v[134:135] op_sel_hi:[1,0]
	v_pk_mul_f32 v[38:39], v[38:39], v[134:135] op_sel_hi:[1,0]
	v_exp_f32_e32 v60, v60
	v_exp_f32_e32 v61, v61
	v_exp_f32_e32 v62, v62
	v_exp_f32_e32 v63, v63
	v_exp_f32_e32 v52, v52
	v_exp_f32_e32 v53, v53
	v_exp_f32_e32 v54, v54
	v_exp_f32_e32 v55, v55
	v_exp_f32_e32 v44, v44
	v_exp_f32_e32 v45, v45
	v_exp_f32_e32 v46, v46
	v_exp_f32_e32 v47, v47
	v_exp_f32_e32 v36, v36
	v_exp_f32_e32 v37, v37
	v_exp_f32_e32 v38, v38
	v_exp_f32_e32 v39, v39
	v_pk_add_f32 v[60:61], v[60:61], v[128:129]
	v_pk_add_f32 v[62:63], v[62:63], v[128:129]
	v_pk_add_f32 v[52:53], v[52:53], v[128:129]
	v_pk_add_f32 v[54:55], v[54:55], v[128:129]
	v_pk_add_f32 v[44:45], v[44:45], v[128:129]
	v_pk_add_f32 v[46:47], v[46:47], v[128:129]
	v_pk_add_f32 v[36:37], v[36:37], v[128:129]
	v_pk_add_f32 v[38:39], v[38:39], v[128:129]
	v_rcp_f32_e32 v60, v60
	v_rcp_f32_e32 v61, v61
	v_rcp_f32_e32 v62, v62
	v_rcp_f32_e32 v63, v63
	v_rcp_f32_e32 v52, v52
	v_rcp_f32_e32 v53, v53
	v_rcp_f32_e32 v54, v54
	v_rcp_f32_e32 v55, v55
	v_rcp_f32_e32 v44, v44
	v_rcp_f32_e32 v45, v45
	v_rcp_f32_e32 v46, v46
	v_rcp_f32_e32 v47, v47
	v_rcp_f32_e32 v36, v36
	v_rcp_f32_e32 v37, v37
	v_rcp_f32_e32 v38, v38
	v_rcp_f32_e32 v39, v39
	v_pk_mul_f32 v[56:57], v[56:57], v[60:61]
	v_pk_mul_f32 v[58:59], v[58:59], v[62:63]
	v_pk_mul_f32 v[48:49], v[48:49], v[52:53]
	v_pk_mul_f32 v[50:51], v[50:51], v[54:55]
	v_pk_mul_f32 v[40:41], v[40:41], v[44:45]
	v_pk_mul_f32 v[42:43], v[42:43], v[46:47]
	v_pk_mul_f32 v[32:33], v[32:33], v[36:37]
	v_pk_mul_f32 v[34:35], v[34:35], v[38:39]
	v_cvt_pk_bf16_f32 v60, v56, v57
	v_cvt_pk_bf16_f32 v61, v58, v59
	v_cvt_pk_bf16_f32 v62, v48, v49
	v_cvt_pk_bf16_f32 v63, v50, v51
	v_cvt_pk_bf16_f32 v44, v40, v41
	v_cvt_pk_bf16_f32 v45, v42, v43
	v_cvt_pk_bf16_f32 v46, v32, v33
	v_cvt_pk_bf16_f32 v47, v34, v35
	v_add_u32_e32 v140, 0xb0000, v132
	global_store_dwordx4 v140, v[60:63], s[8:9]
	v_add_u32_e32 v141, 0xc6000, v132
	global_store_dwordx4 v141, v[44:47], s[8:9]
	v_pk_mul_f32 v[28:29], v[28:29], v[212:213] op_sel_hi:[1,0]
	v_pk_mul_f32 v[30:31], v[30:31], v[212:213] op_sel_hi:[1,0]
	v_pk_mul_f32 v[20:21], v[20:21], v[212:213] op_sel_hi:[1,0]
	v_pk_mul_f32 v[22:23], v[22:23], v[212:213] op_sel_hi:[1,0]
	v_pk_mul_f32 v[12:13], v[12:13], v[214:215] op_sel_hi:[1,0]
	v_pk_mul_f32 v[14:15], v[14:15], v[214:215] op_sel_hi:[1,0]
	v_pk_mul_f32 v[4:5], v[4:5], v[214:215] op_sel_hi:[1,0]
	v_pk_mul_f32 v[6:7], v[6:7], v[214:215] op_sel_hi:[1,0]
	v_pk_mul_f32 v[24:25], v[24:25], v[212:213] op_sel_hi:[1,0]
	v_pk_mul_f32 v[26:27], v[26:27], v[212:213] op_sel_hi:[1,0]
	v_pk_mul_f32 v[16:17], v[16:17], v[212:213] op_sel_hi:[1,0]
	v_pk_mul_f32 v[18:19], v[18:19], v[212:213] op_sel_hi:[1,0]
	v_pk_mul_f32 v[8:9], v[8:9], v[214:215] op_sel_hi:[1,0]
	v_pk_mul_f32 v[10:11], v[10:11], v[214:215] op_sel_hi:[1,0]
	v_pk_mul_f32 v[0:1], v[0:1], v[214:215] op_sel_hi:[1,0]
	v_pk_mul_f32 v[2:3], v[2:3], v[214:215] op_sel_hi:[1,0]
	v_pk_mul_f32 v[24:25], v[28:29], v[24:25]
	v_pk_mul_f32 v[26:27], v[30:31], v[26:27]
	v_pk_mul_f32 v[16:17], v[20:21], v[16:17]
	v_pk_mul_f32 v[18:19], v[22:23], v[18:19]
	v_pk_mul_f32 v[8:9], v[12:13], v[8:9]
	v_pk_mul_f32 v[10:11], v[14:15], v[10:11]
	v_pk_mul_f32 v[0:1], v[4:5], v[0:1]
	v_pk_mul_f32 v[2:3], v[6:7], v[2:3]
	v_pk_mul_f32 v[28:29], v[28:29], v[134:135] op_sel_hi:[1,0]
	v_pk_mul_f32 v[30:31], v[30:31], v[134:135] op_sel_hi:[1,0]
	v_pk_mul_f32 v[20:21], v[20:21], v[134:135] op_sel_hi:[1,0]
	v_pk_mul_f32 v[22:23], v[22:23], v[134:135] op_sel_hi:[1,0]
	v_pk_mul_f32 v[12:13], v[12:13], v[134:135] op_sel_hi:[1,0]
	v_pk_mul_f32 v[14:15], v[14:15], v[134:135] op_sel_hi:[1,0]
	v_pk_mul_f32 v[4:5], v[4:5], v[134:135] op_sel_hi:[1,0]
	v_pk_mul_f32 v[6:7], v[6:7], v[134:135] op_sel_hi:[1,0]
	v_exp_f32_e32 v28, v28
	v_exp_f32_e32 v29, v29
	v_exp_f32_e32 v30, v30
	v_exp_f32_e32 v31, v31
	v_exp_f32_e32 v20, v20
	v_exp_f32_e32 v21, v21
	v_exp_f32_e32 v22, v22
	v_exp_f32_e32 v23, v23
	v_exp_f32_e32 v12, v12
	v_exp_f32_e32 v13, v13
	v_exp_f32_e32 v14, v14
	v_exp_f32_e32 v15, v15
	v_exp_f32_e32 v4, v4
	v_exp_f32_e32 v5, v5
	v_exp_f32_e32 v6, v6
	v_exp_f32_e32 v7, v7
	v_pk_add_f32 v[28:29], v[28:29], v[128:129]
	v_pk_add_f32 v[30:31], v[30:31], v[128:129]
	v_pk_add_f32 v[20:21], v[20:21], v[128:129]
	v_pk_add_f32 v[22:23], v[22:23], v[128:129]
	v_pk_add_f32 v[12:13], v[12:13], v[128:129]
	v_pk_add_f32 v[14:15], v[14:15], v[128:129]
	v_pk_add_f32 v[4:5], v[4:5], v[128:129]
	v_pk_add_f32 v[6:7], v[6:7], v[128:129]
	v_rcp_f32_e32 v28, v28
	v_rcp_f32_e32 v29, v29
	v_rcp_f32_e32 v30, v30
	v_rcp_f32_e32 v31, v31
	v_rcp_f32_e32 v20, v20
	v_rcp_f32_e32 v21, v21
	v_rcp_f32_e32 v22, v22
	v_rcp_f32_e32 v23, v23
	v_rcp_f32_e32 v12, v12
	v_rcp_f32_e32 v13, v13
	v_rcp_f32_e32 v14, v14
	v_rcp_f32_e32 v15, v15
	v_rcp_f32_e32 v4, v4
	v_rcp_f32_e32 v5, v5
	v_rcp_f32_e32 v6, v6
	v_rcp_f32_e32 v7, v7
	v_pk_mul_f32 v[24:25], v[24:25], v[28:29]
	v_pk_mul_f32 v[26:27], v[26:27], v[30:31]
	v_pk_mul_f32 v[16:17], v[16:17], v[20:21]
	v_pk_mul_f32 v[18:19], v[18:19], v[22:23]
	v_pk_mul_f32 v[8:9], v[8:9], v[12:13]
	v_pk_mul_f32 v[10:11], v[10:11], v[14:15]
	v_pk_mul_f32 v[0:1], v[0:1], v[4:5]
	v_pk_mul_f32 v[2:3], v[2:3], v[6:7]
	v_cvt_pk_bf16_f32 v28, v24, v25
	v_cvt_pk_bf16_f32 v29, v26, v27
	v_cvt_pk_bf16_f32 v30, v16, v17
	v_cvt_pk_bf16_f32 v31, v18, v19
	v_cvt_pk_bf16_f32 v12, v8, v9
	v_cvt_pk_bf16_f32 v13, v10, v11
	v_cvt_pk_bf16_f32 v14, v0, v1
	v_cvt_pk_bf16_f32 v15, v2, v3
	v_add_u32_e32 v142, 0xdc000, v132
	global_store_dwordx4 v142, v[28:31], s[8:9]
	v_add_u32_e32 v143, 0xf2000, v132
	global_store_dwordx4 v143, v[12:15], s[8:9]
	s_andn2_b64 vcc, exec, s[36:37]
	s_mov_b64 s[0:1], -1
	s_cbranch_vccnz .LBB0_1643
; #define PG8_WAIT_V(n) asm volatile("s_waitcnt vmcnt(" #n ")" ::: "memory")
; #define PG8_BAR __builtin_amdgcn_s_barrier()
; template <class Epi, class Sched, bool ALIGN_EPI = false, bool SP2 = false>
; __device__ __forceinline__ void gemm_phase(PG8_LAS unsigned char* lds, const Gemm g, const Sched& S, const Epi& E) {
;     ...
;         if constexpr (ALIGN_EPI) { if (wr == 0) PG8_BAR; }
;         if constexpr (!Epi::AFTER_DRAIN) { E(acc, cur, wr, wc, fr, fq); S.done(cur); }
;         if (!has_next) break;
;         { typename Epi::Pre pren = E.issue(nxt, wr, wc, fr, fq); E.finish(acc, pren); }
;         cur = nxt; cA = nA; cB = nB; ++ui;
;         if constexpr (ALIGN_EPI) { if (wr == 1) PG8_BAR; }
;     }
;     PG8_WAIT_V(0);
;     if constexpr (!ALIGN_EPI) { if (wr == 0) PG8_BAR; }
;     PG8_BAR;
	s_andn2_b64 vcc, exec, s[40:41]
	s_cbranch_vccnz .LBB0_1642
	s_barrier
	s_branch .LBB0_1642
